# v47 plus three exit-only copy-out moves taken out of the attention exp/PV section (run on the loop-exit path)
# speedup vs baseline: 1.0045x; 1.0045x over previous
; #define LAS __attribute__((address_space(3)))
; __device__ __forceinline__ unsigned cvtpk2(float lo, float hi) { const f32x2 v = {lo, hi}; const bf16x2_n b = __builtin_convertvector(v, bf16x2_n); return __builtin_bit_cast(unsigned, b); }
; __device__ __forceinline__ void a2_exp_pack(f32x16& st0, f32x16& st1, float& lsum, bf16x8 (&pf)[4]) {
;     float ps = 0.f;
; #pragma unroll
;     for (int r = 0; r < 16; ++r) { st0[r] = __builtin_amdgcn_exp2f(st0[r]); st1[r] = __builtin_amdgcn_exp2f(st1[r]); ps += st0[r] + st1[r]; }
;     lsum += ps;
;     u32x4 w;
;     w.x = cvtpk2(st0[0], st0[1]); w.y = cvtpk2(st0[2], st0[3]); w.z = cvtpk2(st0[4], st0[5]); w.w = cvtpk2(st0[6], st0[7]); pf[0] = __builtin_bit_cast(bf16x8, w);
;     w.x = cvtpk2(st0[8], st0[9]); w.y = cvtpk2(st0[10], st0[11]); w.z = cvtpk2(st0[12], st0[13]); w.w = cvtpk2(st0[14], st0[15]); pf[1] = __builtin_bit_cast(bf16x8, w);
;     w.x = cvtpk2(st1[0], st1[1]); w.y = cvtpk2(st1[2], st1[3]); w.z = cvtpk2(st1[4], st1[5]); w.w = cvtpk2(st1[6], st1[7]); pf[2] = __builtin_bit_cast(bf16x8, w);
;     w.x = cvtpk2(st1[8], st1[9]); w.y = cvtpk2(st1[10], st1[11]); w.z = cvtpk2(st1[12], st1[13]); w.w = cvtpk2(st1[14], st1[15]); pf[3] = __builtin_bit_cast(bf16x8, w);
; }
; __device__ __forceinline__ void a2_pv(const LAS unsigned char* vb, const bf16x8 (&pf)[4], f32x16& ot0, f32x16& ot1) {
; #pragma unroll
;     for (int s = 0; s < 4; ++s) {
;         const s16x4 a00 = __builtin_bit_cast(s16x4, __builtin_amdgcn_ds_read_tr16_b64_v4i16((LAS s16x4*)(vb + (16 * s) * 64)));
;         const s16x4 a01 = __builtin_bit_cast(s16x4, __builtin_amdgcn_ds_read_tr16_b64_v4i16((LAS s16x4*)(vb + (16 * s + 8) * 64)));
;         const s16x4 a10 = __builtin_bit_cast(s16x4, __builtin_amdgcn_ds_read_tr16_b64_v4i16((LAS s16x4*)(vb + 8192 + (16 * s) * 64)));
;         const s16x4 a11 = __builtin_bit_cast(s16x4, __builtin_amdgcn_ds_read_tr16_b64_v4i16((LAS s16x4*)(vb + 8192 + (16 * s + 8) * 64)));
;         const bf16x8 va0 = (bf16x8){a00[0], a00[1], a00[2], a00[3], a01[0], a01[1], a01[2], a01[3]};
;         const bf16x8 va1 = (bf16x8){a10[0], a10[1], a10[2], a10[3], a11[0], a11[1], a11[2], a11[3]};
;         ot0 = __builtin_amdgcn_mfma_f32_32x32x16_bf16(va0, pf[s], ot0, 0, 0, 0); ot1 = __builtin_amdgcn_mfma_f32_32x32x16_bf16(va1, pf[s], ot1, 0, 0, 0); }
; }
.LBB0_832:
	v_add_u32_e32 v0, v2, v218
	v_exp_f32_e32 v199, v112
	v_exp_f32_e32 v7, v96
	v_exp_f32_e32 v113, v113
	v_exp_f32_e32 v9, v97
	v_exp_f32_e32 v201, v114
	v_exp_f32_e32 v3, v98
	v_exp_f32_e32 v115, v115
	v_exp_f32_e32 v5, v99
	v_exp_f32_e32 v203, v116
	v_exp_f32_e32 v15, v117
	v_exp_f32_e32 v13, v118
	v_exp_f32_e32 v11, v119
	s_waitcnt vmcnt(0)
	ds_read_b64_tr_b16 v[96:97], v0 offset:26624
	ds_read_b64_tr_b16 v[98:99], v0 offset:27136
	ds_read_b64_tr_b16 v[214:215], v0 offset:34816
	ds_read_b64_tr_b16 v[216:217], v0 offset:35328
	ds_read_b64_tr_b16 v[224:225], v0 offset:27648
	ds_read_b64_tr_b16 v[226:227], v0 offset:28160
	v_cvt_pk_bf16_f32 v210, v199, v113
	v_cvt_pk_bf16_f32 v211, v201, v115
	v_cvt_pk_bf16_f32 v212, v203, v15
	v_cvt_pk_bf16_f32 v213, v13, v11
	v_exp_f32_e32 v209, v120
	v_exp_f32_e32 v207, v121
	s_waitcnt lgkmcnt(4)
	v_mfma_f32_32x32x16_bf16 v[16:31], v[96:99], v[210:213], v[16:31]
	v_exp_f32_e32 v205, v122
	v_exp_f32_e32 v121, v123
	v_exp_f32_e32 v117, v124
	ds_read_b64_tr_b16 v[228:229], v0 offset:35840
	ds_read_b64_tr_b16 v[230:231], v0 offset:36352
	v_exp_f32_e32 v119, v125
	v_exp_f32_e32 v99, v126
	v_exp_f32_e32 v97, v127
	s_waitcnt lgkmcnt(4)
	v_mfma_f32_32x32x16_bf16 v[32:47], v[214:217], v[210:213], v[32:47]
	v_cvt_pk_bf16_f32 v232, v209, v207
	v_cvt_pk_bf16_f32 v233, v205, v121
	v_cvt_pk_bf16_f32 v234, v117, v119
	v_cvt_pk_bf16_f32 v235, v99, v97
	v_exp_f32_e32 v125, v100
	v_exp_f32_e32 v213, v101
	v_exp_f32_e32 v211, v102
	s_waitcnt lgkmcnt(2)
	v_mfma_f32_32x32x16_bf16 v[16:31], v[224:227], v[232:235], v[16:31]
	v_exp_f32_e32 v217, v103
	ds_read_b64_tr_b16 v[224:225], v0 offset:28672
	ds_read_b64_tr_b16 v[226:227], v0 offset:29184
	v_cvt_pk_bf16_f32 v100, v7, v9
	v_cvt_pk_bf16_f32 v101, v3, v5
	v_cvt_pk_bf16_f32 v102, v125, v213
	v_cvt_pk_bf16_f32 v103, v211, v217
	v_exp_f32_e32 v123, v104
	s_waitcnt lgkmcnt(2)
	v_mfma_f32_32x32x16_bf16 v[32:47], v[228:231], v[232:235], v[32:47]
	ds_read_b64_tr_b16 v[228:229], v0 offset:36864
	ds_read_b64_tr_b16 v[230:231], v0 offset:37376
	ds_read_b64_tr_b16 v[232:233], v0 offset:29696
	ds_read_b64_tr_b16 v[234:235], v0 offset:30208
	v_exp_f32_e32 v127, v105
	v_exp_f32_e32 v105, v106
	v_exp_f32_e32 v215, v107
	v_exp_f32_e32 v107, v108
	v_exp_f32_e32 v109, v109
	v_exp_f32_e32 v198, v64
	s_waitcnt lgkmcnt(4)
	v_mfma_f32_32x32x16_bf16 v[16:31], v[224:227], v[100:103], v[16:31]
	ds_read_b64_tr_b16 v[224:225], v0 offset:37888
	ds_read_b64_tr_b16 v[226:227], v0 offset:38400
	v_exp_f32_e32 v6, v80
	v_exp_f32_e32 v112, v65
	v_exp_f32_e32 v8, v81
	v_exp_f32_e32 v200, v66
	v_exp_f32_e32 v2, v82
	v_exp_f32_e32 v114, v67
	s_waitcnt lgkmcnt(4)
	v_mfma_f32_32x32x16_bf16 v[32:47], v[228:231], v[100:103], v[32:47]
	v_exp_f32_e32 v103, v110
	v_exp_f32_e32 v101, v111
	v_exp_f32_e32 v4, v83
	v_cvt_pk_bf16_f32 v228, v123, v127
	v_cvt_pk_bf16_f32 v229, v105, v215
	v_cvt_pk_bf16_f32 v230, v107, v109
	v_cvt_pk_bf16_f32 v231, v103, v101
	v_pk_add_f32 v[64:65], v[6:7], v[198:199]
	v_pk_add_f32 v[66:67], v[8:9], v[112:113]
	s_waitcnt lgkmcnt(2)
	v_mfma_f32_32x32x16_bf16 v[16:31], v[232:235], v[228:231], v[16:31]
	v_add_f32_e64 v64, v64, 0
	v_add_f32_e64 v65, v65, 0
	v_exp_f32_e32 v202, v68
	v_pk_add_f32 v[64:65], v[66:67], v[64:65]
	v_pk_add_f32 v[66:67], v[2:3], v[200:201]
	v_exp_f32_e32 v14, v69
	v_pk_add_f32 v[64:65], v[66:67], v[64:65]
	v_pk_add_f32 v[66:67], v[4:5], v[114:115]
	s_waitcnt lgkmcnt(0)
	v_mfma_f32_32x32x16_bf16 v[32:47], v[224:227], v[228:231], v[32:47]
	v_add_f32_e64 v110, v66, v64
	v_add_f32_e64 v111, v67, v65
	v_exp_f32_e32 v12, v70
	v_exp_f32_e32 v10, v71
	ds_read_b64_tr_b16 v[64:65], v0 offset:30720
	ds_read_b64_tr_b16 v[66:67], v0 offset:31232
	v_exp_f32_e32 v124, v84
	v_exp_f32_e32 v208, v72
	v_exp_f32_e32 v206, v73
	v_exp_f32_e32 v204, v74
	v_exp_f32_e32 v120, v75
	ds_read_b64_tr_b16 v[72:73], v0 offset:38912
	ds_read_b64_tr_b16 v[74:75], v0 offset:39424
	ds_read_b64_tr_b16 v[80:81], v0 offset:31744
	ds_read_b64_tr_b16 v[82:83], v0 offset:32256
	v_exp_f32_e32 v212, v85
	v_cvt_pk_bf16_f32 v68, v198, v112
	v_cvt_pk_bf16_f32 v69, v200, v114
	v_cvt_pk_bf16_f32 v70, v202, v14
	v_cvt_pk_bf16_f32 v71, v12, v10
	v_pk_add_f32 v[220:221], v[124:125], v[202:203]
	v_exp_f32_e32 v210, v86
	s_waitcnt lgkmcnt(4)
	v_mfma_f32_32x32x16_bf16 v[16:31], v[64:67], v[68:71], v[16:31]
	v_add_f32_e64 v64, v220, v110
	v_add_f32_e64 v65, v221, v111
	v_add_f32_e64 v14, v212, v14
	v_add_f32_e64 v15, v213, v15
	v_exp_f32_e32 v216, v87
	v_exp_f32_e32 v116, v76
	v_exp_f32_e32 v118, v77
	v_exp_f32_e32 v98, v78
	v_exp_f32_e32 v96, v79
	s_waitcnt lgkmcnt(2)
; #define LAS __attribute__((address_space(3)))
; __device__ __forceinline__ void a2_pv(const LAS unsigned char* vb, const bf16x8 (&pf)[4], f32x16& ot0, f32x16& ot1) {
; #pragma unroll
;     for (int s = 0; s < 4; ++s) {
;         const s16x4 a00 = __builtin_bit_cast(s16x4, __builtin_amdgcn_ds_read_tr16_b64_v4i16((LAS s16x4*)(vb + (16 * s) * 64)));
;         const s16x4 a01 = __builtin_bit_cast(s16x4, __builtin_amdgcn_ds_read_tr16_b64_v4i16((LAS s16x4*)(vb + (16 * s + 8) * 64)));
;         const s16x4 a10 = __builtin_bit_cast(s16x4, __builtin_amdgcn_ds_read_tr16_b64_v4i16((LAS s16x4*)(vb + 8192 + (16 * s) * 64)));
;         const s16x4 a11 = __builtin_bit_cast(s16x4, __builtin_amdgcn_ds_read_tr16_b64_v4i16((LAS s16x4*)(vb + 8192 + (16 * s + 8) * 64)));
;         const bf16x8 va0 = (bf16x8){a00[0], a00[1], a00[2], a00[3], a01[0], a01[1], a01[2], a01[3]};
;         const bf16x8 va1 = (bf16x8){a10[0], a10[1], a10[2], a10[3], a11[0], a11[1], a11[2], a11[3]};
;         ot0 = __builtin_amdgcn_mfma_f32_32x32x16_bf16(va0, pf[s], ot0, 0, 0, 0); ot1 = __builtin_amdgcn_mfma_f32_32x32x16_bf16(va1, pf[s], ot1, 0, 0, 0); }
; }
; __device__ __forceinline__ void attn2_unit(bf16_t* Z, const bf16_t* Hb, const float* rc, const float* rs, LAS unsigned char* lds, int b, int h, int qblk) {
;     ...
;             a2_exp_pack(sa0, sa1, lsum, pa);
;             a2_pv(vb, pa, ot0, ot1);
;             a2_exp_pack(sb0, sb1, lsum, pb);
;             a2_pv(vb + 64 * 64, pb, ot0, ot1);
;         } else if (2 * kp <= cw) {
;             f32x16 sa0, sa1; bf16x8 pa[4];
;             a2_qk(kb, qf, cneg, sa0, sa1);
;             const float mt = a2_max(sa0, sa1);
;             if (kp == 0 || __builtin_amdgcn_ballot_w64(mt > 8.f) != 0ull) {
;                 const float delta = (kp == 0) ? mt : fmaxf(mt, 0.f), alpha = (kp == 0) ? 0.f : __builtin_amdgcn_exp2f(-delta);
;                 mrun += delta; lsum *= alpha;
; #pragma unroll
;                 for (int r = 0; r < 16; ++r) { ot0[r] *= alpha; ot1[r] *= alpha; sa0[r] -= delta; sa1[r] -= delta; cneg[r] = -mrun; }
;             }
;             a2_exp_pack(sa0, sa1, lsum, pa);
;             a2_pv(vb, pa, ot0, ot1);
;         }
;         __syncthreads();
;     }
	v_mfma_f32_32x32x16_bf16 v[32:47], v[72:75], v[68:71], v[32:47]
	v_add_f32_e64 v14, v14, v64
	v_add_f32_e64 v15, v15, v65
	ds_read_b64_tr_b16 v[64:65], v0 offset:39936
	ds_read_b64_tr_b16 v[66:67], v0 offset:40448
	v_exp_f32_e32 v122, v88
	v_pk_add_f32 v[12:13], v[210:211], v[12:13]
	v_pk_add_f32 v[68:69], v[216:217], v[10:11]
	v_pk_add_f32 v[14:15], v[12:13], v[14:15]
	v_cvt_pk_bf16_f32 v10, v208, v206
	v_cvt_pk_bf16_f32 v11, v204, v120
	v_cvt_pk_bf16_f32 v12, v116, v118
	v_cvt_pk_bf16_f32 v13, v98, v96
	v_pk_add_f32 v[14:15], v[68:69], v[14:15]
	v_pk_add_f32 v[68:69], v[122:123], v[208:209]
	s_waitcnt lgkmcnt(2)
	v_mfma_f32_32x32x16_bf16 v[16:31], v[80:83], v[10:13], v[16:31]
	v_add_f32_e64 v14, v68, v14
	v_add_f32_e64 v15, v69, v15
	ds_read_b64_tr_b16 v[68:69], v0 offset:32768
	ds_read_b64_tr_b16 v[70:71], v0 offset:33280
	v_exp_f32_e32 v126, v89
	v_exp_f32_e32 v104, v90
	v_cvt_pk_bf16_f32 v7, v2, v4
	v_exp_f32_e32 v214, v91
	v_cvt_pk_bf16_f32 v6, v6, v8
	s_waitcnt lgkmcnt(2)
	v_mfma_f32_32x32x16_bf16 v[32:47], v[64:67], v[10:13], v[32:47]
	ds_read_b64_tr_b16 v[2:3], v0 offset:40960
	ds_read_b64_tr_b16 v[4:5], v0 offset:41472
	ds_read_b64_tr_b16 v[10:11], v0 offset:33792
	ds_read_b64_tr_b16 v[12:13], v0 offset:34304
	v_cvt_pk_bf16_f32 v8, v124, v212
	v_cvt_pk_bf16_f32 v9, v210, v216
	v_pk_add_f32 v[72:73], v[126:127], v[206:207]
	v_pk_add_f32 v[64:65], v[104:105], v[204:205]
	v_pk_add_f32 v[14:15], v[72:73], v[14:15]
	v_exp_f32_e32 v106, v92
	s_waitcnt lgkmcnt(4)
	v_mfma_f32_32x32x16_bf16 v[16:31], v[68:71], v[6:9], v[16:31]
	v_add_f32_e64 v14, v64, v14
	v_add_f32_e64 v15, v65, v15
	v_add_f32_e64 v64, v214, v120
	v_add_f32_e64 v65, v215, v121
	v_exp_f32_e32 v108, v93
	v_exp_f32_e32 v102, v94
	v_exp_f32_e32 v100, v95
	v_pk_add_f32 v[14:15], v[64:65], v[14:15]
	ds_read_b64_tr_b16 v[64:65], v0 offset:41984
	ds_read_b64_tr_b16 v[66:67], v0 offset:42496
	s_waitcnt lgkmcnt(4)
	v_mfma_f32_32x32x16_bf16 v[32:47], v[2:5], v[6:9], v[32:47]
	v_add_f32_e64 v2, v106, v116
	v_add_f32_e64 v3, v107, v117
	v_cvt_pk_bf16_f32 v4, v106, v108
	v_add_f32_e64 v6, v2, v14
	v_add_f32_e64 v7, v3, v15
	v_cvt_pk_bf16_f32 v2, v122, v126
	v_cvt_pk_bf16_f32 v3, v104, v214
	v_cvt_pk_bf16_f32 v5, v102, v100
	v_pk_add_f32 v[8:9], v[108:109], v[118:119]
	s_waitcnt lgkmcnt(2)
	v_mfma_f32_32x32x16_bf16 v[16:31], v[10:13], v[2:5], v[16:31]
	v_add_f32_e64 v6, v8, v6
	v_add_f32_e64 v7, v9, v7
	v_add_f32_e64 v8, v102, v98
	v_add_f32_e64 v9, v103, v99
	v_pk_add_f32 v[6:7], v[8:9], v[6:7]
	v_pk_add_f32 v[8:9], v[100:101], v[96:97]
	v_pk_add_f32 v[6:7], v[8:9], v[6:7]
	s_waitcnt lgkmcnt(0)
	v_mfma_f32_32x32x16_bf16 v[32:47], v[64:67], v[2:5], v[32:47]
	v_add_f32_e32 v0, v169, v7
	v_add_f32_e32 v0, v6, v0
	s_add_i32 s65, s65, 1
	s_add_i32 s69, s69, 2
	s_add_i32 s6, s43, s65
	v_lshl_add_u64 v[176:177], v[176:177], 0, v[174:175]
	v_lshl_add_u64 v[178:179], v[178:179], 0, s[20:21]
	v_lshl_add_u64 v[180:181], v[180:181], 0, s[20:21]
	v_lshl_add_u64 v[184:185], v[184:185], 0, v[182:183]
	v_lshl_add_u64 v[188:189], v[188:189], 0, v[186:187]
	s_cmp_lg_u32 s6, 1
	v_lshl_add_u64 v[196:197], v[196:197], 0, v[190:191]
	s_waitcnt vmcnt(0) lgkmcnt(0)
	s_barrier
	s_cbranch_scc0 .Lattn_exit_0
	v_mov_b32_e32 v169, v0
	s_bitcmp1_b32 s65, 0
	s_cselect_b32 s6, 0, 0xa800
	s_cmp_ge_u32 s65, s36
	s_cbranch_scc0 .LBB0_810
	s_branch .LBB0_813
.Lattn_exit_0:
	s_nop 7
	s_nop 7
	v_mov_b32_e32 v14, v55
	v_mov_b32_e32 v10, v59
	v_mov_b32_e32 v11, v58
	v_mov_b64_e32 v[110:111], v[30:31]
	v_mov_b32_e32 v6, v63
	v_mov_b32_e32 v7, v62
	v_mov_b32_e32 v8, v61
	v_mov_b32_e32 v9, v60
	v_mov_b64_e32 v[126:127], v[46:47]
	v_mov_b32_e32 v12, v57
	v_mov_b32_e32 v13, v56
	v_mov_b32_e32 v15, v54
	v_mov_b32_e32 v171, v53
	v_mov_b32_e32 v198, v52
	v_mov_b32_e32 v199, v51
	v_mov_b32_e32 v200, v50
	v_mov_b32_e32 v201, v49
	v_mov_b32_e32 v4, v48
	v_mov_b32_e32 v5, v165
	v_mov_b64_e32 v[108:109], v[28:29]
	v_mov_b64_e32 v[106:107], v[26:27]
	v_mov_b64_e32 v[104:105], v[24:25]
	v_mov_b64_e32 v[102:103], v[22:23]
	v_mov_b64_e32 v[100:101], v[20:21]
	v_mov_b64_e32 v[98:99], v[18:19]
	v_mov_b64_e32 v[96:97], v[16:17]
	v_mov_b64_e32 v[124:125], v[44:45]
	v_mov_b64_e32 v[122:123], v[42:43]
	v_mov_b64_e32 v[120:121], v[40:41]
	v_mov_b64_e32 v[118:119], v[38:39]
	v_mov_b64_e32 v[116:117], v[36:37]
	v_mov_b64_e32 v[114:115], v[34:35]
	v_mov_b64_e32 v[112:113], v[32:33]
	s_branch .LBB0_837

; #define LAS __attribute__((address_space(3)))
; __device__ __forceinline__ unsigned cvtpk2(float lo, float hi) { const f32x2 v = {lo, hi}; const bf16x2_n b = __builtin_convertvector(v, bf16x2_n); return __builtin_bit_cast(unsigned, b); }
; __device__ __forceinline__ void a2_exp_pack(f32x16& st0, f32x16& st1, float& lsum, bf16x8 (&pf)[4]) {
;     float ps = 0.f;
; #pragma unroll
;     for (int r = 0; r < 16; ++r) { st0[r] = __builtin_amdgcn_exp2f(st0[r]); st1[r] = __builtin_amdgcn_exp2f(st1[r]); ps += st0[r] + st1[r]; }
;     lsum += ps;
;     u32x4 w;
;     w.x = cvtpk2(st0[0], st0[1]); w.y = cvtpk2(st0[2], st0[3]); w.z = cvtpk2(st0[4], st0[5]); w.w = cvtpk2(st0[6], st0[7]); pf[0] = __builtin_bit_cast(bf16x8, w);
;     w.x = cvtpk2(st0[8], st0[9]); w.y = cvtpk2(st0[10], st0[11]); w.z = cvtpk2(st0[12], st0[13]); w.w = cvtpk2(st0[14], st0[15]); pf[1] = __builtin_bit_cast(bf16x8, w);
;     w.x = cvtpk2(st1[0], st1[1]); w.y = cvtpk2(st1[2], st1[3]); w.z = cvtpk2(st1[4], st1[5]); w.w = cvtpk2(st1[6], st1[7]); pf[2] = __builtin_bit_cast(bf16x8, w);
;     w.x = cvtpk2(st1[8], st1[9]); w.y = cvtpk2(st1[10], st1[11]); w.z = cvtpk2(st1[12], st1[13]); w.w = cvtpk2(st1[14], st1[15]); pf[3] = __builtin_bit_cast(bf16x8, w);
; }
; __device__ __forceinline__ void a2_pv(const LAS unsigned char* vb, const bf16x8 (&pf)[4], f32x16& ot0, f32x16& ot1) {
; #pragma unroll
;     for (int s = 0; s < 4; ++s) {
;         const s16x4 a00 = __builtin_bit_cast(s16x4, __builtin_amdgcn_ds_read_tr16_b64_v4i16((LAS s16x4*)(vb + (16 * s) * 64)));
;         const s16x4 a01 = __builtin_bit_cast(s16x4, __builtin_amdgcn_ds_read_tr16_b64_v4i16((LAS s16x4*)(vb + (16 * s + 8) * 64)));
;         const s16x4 a10 = __builtin_bit_cast(s16x4, __builtin_amdgcn_ds_read_tr16_b64_v4i16((LAS s16x4*)(vb + 8192 + (16 * s) * 64)));
;         const s16x4 a11 = __builtin_bit_cast(s16x4, __builtin_amdgcn_ds_read_tr16_b64_v4i16((LAS s16x4*)(vb + 8192 + (16 * s + 8) * 64)));
;         const bf16x8 va0 = (bf16x8){a00[0], a00[1], a00[2], a00[3], a01[0], a01[1], a01[2], a01[3]};
;         const bf16x8 va1 = (bf16x8){a10[0], a10[1], a10[2], a10[3], a11[0], a11[1], a11[2], a11[3]};
;         ot0 = __builtin_amdgcn_mfma_f32_32x32x16_bf16(va0, pf[s], ot0, 0, 0, 0); ot1 = __builtin_amdgcn_mfma_f32_32x32x16_bf16(va1, pf[s], ot1, 0, 0, 0); }
; }
.LBB0_878:
	v_add_u32_e32 v0, v2, v218
	v_exp_f32_e32 v197, v112
	v_exp_f32_e32 v7, v96
	v_exp_f32_e32 v113, v113
	v_exp_f32_e32 v9, v97
	v_exp_f32_e32 v199, v114
	v_exp_f32_e32 v3, v98
	v_exp_f32_e32 v115, v115
	v_exp_f32_e32 v5, v99
	v_exp_f32_e32 v201, v116
	v_exp_f32_e32 v15, v117
	v_exp_f32_e32 v13, v118
	v_exp_f32_e32 v11, v119
	s_waitcnt vmcnt(0)
	ds_read_b64_tr_b16 v[96:97], v0 offset:26624
	ds_read_b64_tr_b16 v[98:99], v0 offset:27136
	ds_read_b64_tr_b16 v[212:213], v0 offset:34816
	ds_read_b64_tr_b16 v[214:215], v0 offset:35328
	ds_read_b64_tr_b16 v[224:225], v0 offset:27648
	ds_read_b64_tr_b16 v[226:227], v0 offset:28160
	v_cvt_pk_bf16_f32 v208, v197, v113
	v_cvt_pk_bf16_f32 v209, v199, v115
	v_cvt_pk_bf16_f32 v210, v201, v15
	v_cvt_pk_bf16_f32 v211, v13, v11
	v_exp_f32_e32 v207, v120
	v_exp_f32_e32 v205, v121
	s_waitcnt lgkmcnt(4)
	v_mfma_f32_32x32x16_bf16 v[16:31], v[96:99], v[208:211], v[16:31]
	v_exp_f32_e32 v203, v122
	v_exp_f32_e32 v121, v123
	v_exp_f32_e32 v117, v124
	ds_read_b64_tr_b16 v[228:229], v0 offset:35840
	ds_read_b64_tr_b16 v[230:231], v0 offset:36352
	v_exp_f32_e32 v119, v125
	v_exp_f32_e32 v99, v126
	v_exp_f32_e32 v97, v127
	s_waitcnt lgkmcnt(4)
	v_mfma_f32_32x32x16_bf16 v[32:47], v[212:215], v[208:211], v[32:47]
	v_cvt_pk_bf16_f32 v232, v207, v205
	v_cvt_pk_bf16_f32 v233, v203, v121
	v_cvt_pk_bf16_f32 v234, v117, v119
	v_cvt_pk_bf16_f32 v235, v99, v97
	v_exp_f32_e32 v125, v100
	v_exp_f32_e32 v211, v101
	v_exp_f32_e32 v209, v102
	s_waitcnt lgkmcnt(2)
	v_mfma_f32_32x32x16_bf16 v[16:31], v[224:227], v[232:235], v[16:31]
	v_exp_f32_e32 v215, v103
	ds_read_b64_tr_b16 v[224:225], v0 offset:28672
	ds_read_b64_tr_b16 v[226:227], v0 offset:29184
	v_cvt_pk_bf16_f32 v100, v7, v9
	v_cvt_pk_bf16_f32 v101, v3, v5
	v_cvt_pk_bf16_f32 v102, v125, v211
	v_cvt_pk_bf16_f32 v103, v209, v215
	v_exp_f32_e32 v123, v104
	s_waitcnt lgkmcnt(2)
	v_mfma_f32_32x32x16_bf16 v[32:47], v[228:231], v[232:235], v[32:47]
	ds_read_b64_tr_b16 v[228:229], v0 offset:36864
	ds_read_b64_tr_b16 v[230:231], v0 offset:37376
	ds_read_b64_tr_b16 v[232:233], v0 offset:29696
	ds_read_b64_tr_b16 v[234:235], v0 offset:30208
	v_exp_f32_e32 v127, v105
	v_exp_f32_e32 v105, v106
	v_exp_f32_e32 v213, v107
	v_exp_f32_e32 v107, v108
	v_exp_f32_e32 v109, v109
	v_exp_f32_e32 v196, v64
	s_waitcnt lgkmcnt(4)
	v_mfma_f32_32x32x16_bf16 v[16:31], v[224:227], v[100:103], v[16:31]
	ds_read_b64_tr_b16 v[224:225], v0 offset:37888
	ds_read_b64_tr_b16 v[226:227], v0 offset:38400
	v_exp_f32_e32 v6, v80
	v_exp_f32_e32 v112, v65
	v_exp_f32_e32 v8, v81
	v_exp_f32_e32 v198, v66
	v_exp_f32_e32 v2, v82
	v_exp_f32_e32 v114, v67
	s_waitcnt lgkmcnt(4)
	v_mfma_f32_32x32x16_bf16 v[32:47], v[228:231], v[100:103], v[32:47]
	v_exp_f32_e32 v103, v110
	v_exp_f32_e32 v101, v111
	v_exp_f32_e32 v4, v83
	v_cvt_pk_bf16_f32 v228, v123, v127
	v_cvt_pk_bf16_f32 v229, v105, v213
	v_cvt_pk_bf16_f32 v230, v107, v109
	v_cvt_pk_bf16_f32 v231, v103, v101
	v_pk_add_f32 v[64:65], v[6:7], v[196:197]
	v_pk_add_f32 v[66:67], v[8:9], v[112:113]
	s_waitcnt lgkmcnt(2)
	v_mfma_f32_32x32x16_bf16 v[16:31], v[232:235], v[228:231], v[16:31]
	v_add_f32_e64 v64, v64, 0
	v_add_f32_e64 v65, v65, 0
	v_exp_f32_e32 v200, v68
	v_pk_add_f32 v[64:65], v[66:67], v[64:65]
	v_pk_add_f32 v[66:67], v[2:3], v[198:199]
	v_exp_f32_e32 v14, v69
	v_pk_add_f32 v[64:65], v[66:67], v[64:65]
	v_pk_add_f32 v[66:67], v[4:5], v[114:115]
	s_waitcnt lgkmcnt(0)
	v_mfma_f32_32x32x16_bf16 v[32:47], v[224:227], v[228:231], v[32:47]
	v_add_f32_e64 v110, v66, v64
	v_add_f32_e64 v111, v67, v65
	v_exp_f32_e32 v12, v70
	v_exp_f32_e32 v10, v71
	ds_read_b64_tr_b16 v[64:65], v0 offset:30720
	ds_read_b64_tr_b16 v[66:67], v0 offset:31232
	v_exp_f32_e32 v124, v84
	v_exp_f32_e32 v206, v72
	v_exp_f32_e32 v204, v73
	v_exp_f32_e32 v202, v74
	v_exp_f32_e32 v120, v75
	ds_read_b64_tr_b16 v[72:73], v0 offset:38912
	ds_read_b64_tr_b16 v[74:75], v0 offset:39424
	ds_read_b64_tr_b16 v[80:81], v0 offset:31744
	ds_read_b64_tr_b16 v[82:83], v0 offset:32256
	v_exp_f32_e32 v210, v85
	v_cvt_pk_bf16_f32 v68, v196, v112
	v_cvt_pk_bf16_f32 v69, v198, v114
	v_cvt_pk_bf16_f32 v70, v200, v14
	v_cvt_pk_bf16_f32 v71, v12, v10
	v_pk_add_f32 v[216:217], v[124:125], v[200:201]
	v_exp_f32_e32 v208, v86
	s_waitcnt lgkmcnt(4)
	v_mfma_f32_32x32x16_bf16 v[16:31], v[64:67], v[68:71], v[16:31]
	v_add_f32_e64 v64, v216, v110
	v_add_f32_e64 v65, v217, v111
	v_add_f32_e64 v14, v210, v14
	v_add_f32_e64 v15, v211, v15
	v_exp_f32_e32 v214, v87
	v_exp_f32_e32 v116, v76
	v_exp_f32_e32 v118, v77
	v_exp_f32_e32 v98, v78
	v_exp_f32_e32 v96, v79
	s_waitcnt lgkmcnt(2)
; #define LAS __attribute__((address_space(3)))
; __device__ __forceinline__ void a2_pv(const LAS unsigned char* vb, const bf16x8 (&pf)[4], f32x16& ot0, f32x16& ot1) {
; #pragma unroll
;     for (int s = 0; s < 4; ++s) {
;         const s16x4 a00 = __builtin_bit_cast(s16x4, __builtin_amdgcn_ds_read_tr16_b64_v4i16((LAS s16x4*)(vb + (16 * s) * 64)));
;         const s16x4 a01 = __builtin_bit_cast(s16x4, __builtin_amdgcn_ds_read_tr16_b64_v4i16((LAS s16x4*)(vb + (16 * s + 8) * 64)));
;         const s16x4 a10 = __builtin_bit_cast(s16x4, __builtin_amdgcn_ds_read_tr16_b64_v4i16((LAS s16x4*)(vb + 8192 + (16 * s) * 64)));
;         const s16x4 a11 = __builtin_bit_cast(s16x4, __builtin_amdgcn_ds_read_tr16_b64_v4i16((LAS s16x4*)(vb + 8192 + (16 * s + 8) * 64)));
;         const bf16x8 va0 = (bf16x8){a00[0], a00[1], a00[2], a00[3], a01[0], a01[1], a01[2], a01[3]};
;         const bf16x8 va1 = (bf16x8){a10[0], a10[1], a10[2], a10[3], a11[0], a11[1], a11[2], a11[3]};
;         ot0 = __builtin_amdgcn_mfma_f32_32x32x16_bf16(va0, pf[s], ot0, 0, 0, 0); ot1 = __builtin_amdgcn_mfma_f32_32x32x16_bf16(va1, pf[s], ot1, 0, 0, 0); }
; }
; __device__ __forceinline__ void attn2_unit(bf16_t* Z, const bf16_t* Hb, const float* rc, const float* rs, LAS unsigned char* lds, int b, int h, int qblk) {
;     ...
;             a2_exp_pack(sa0, sa1, lsum, pa);
;             a2_pv(vb, pa, ot0, ot1);
;             a2_exp_pack(sb0, sb1, lsum, pb);
;             a2_pv(vb + 64 * 64, pb, ot0, ot1);
;         } else if (2 * kp <= cw) {
;             f32x16 sa0, sa1; bf16x8 pa[4];
;             a2_qk(kb, qf, cneg, sa0, sa1);
;             const float mt = a2_max(sa0, sa1);
;             if (kp == 0 || __builtin_amdgcn_ballot_w64(mt > 8.f) != 0ull) {
;                 const float delta = (kp == 0) ? mt : fmaxf(mt, 0.f), alpha = (kp == 0) ? 0.f : __builtin_amdgcn_exp2f(-delta);
;                 mrun += delta; lsum *= alpha;
; #pragma unroll
;                 for (int r = 0; r < 16; ++r) { ot0[r] *= alpha; ot1[r] *= alpha; sa0[r] -= delta; sa1[r] -= delta; cneg[r] = -mrun; }
;             }
;             a2_exp_pack(sa0, sa1, lsum, pa);
;             a2_pv(vb, pa, ot0, ot1);
;         }
;         __syncthreads();
;     }
	v_mfma_f32_32x32x16_bf16 v[32:47], v[72:75], v[68:71], v[32:47]
	v_add_f32_e64 v14, v14, v64
	v_add_f32_e64 v15, v15, v65
	ds_read_b64_tr_b16 v[64:65], v0 offset:39936
	ds_read_b64_tr_b16 v[66:67], v0 offset:40448
	v_exp_f32_e32 v122, v88
	v_pk_add_f32 v[12:13], v[208:209], v[12:13]
	v_pk_add_f32 v[68:69], v[214:215], v[10:11]
	v_pk_add_f32 v[14:15], v[12:13], v[14:15]
	v_cvt_pk_bf16_f32 v10, v206, v204
	v_cvt_pk_bf16_f32 v11, v202, v120
	v_cvt_pk_bf16_f32 v12, v116, v118
	v_cvt_pk_bf16_f32 v13, v98, v96
	v_pk_add_f32 v[14:15], v[68:69], v[14:15]
	v_pk_add_f32 v[68:69], v[122:123], v[206:207]
	s_waitcnt lgkmcnt(2)
	v_mfma_f32_32x32x16_bf16 v[16:31], v[80:83], v[10:13], v[16:31]
	v_add_f32_e64 v14, v68, v14
	v_add_f32_e64 v15, v69, v15
	ds_read_b64_tr_b16 v[68:69], v0 offset:32768
	ds_read_b64_tr_b16 v[70:71], v0 offset:33280
	v_exp_f32_e32 v126, v89
	v_exp_f32_e32 v104, v90
	v_cvt_pk_bf16_f32 v7, v2, v4
	v_exp_f32_e32 v212, v91
	v_cvt_pk_bf16_f32 v6, v6, v8
	s_waitcnt lgkmcnt(2)
	v_mfma_f32_32x32x16_bf16 v[32:47], v[64:67], v[10:13], v[32:47]
	ds_read_b64_tr_b16 v[2:3], v0 offset:40960
	ds_read_b64_tr_b16 v[4:5], v0 offset:41472
	ds_read_b64_tr_b16 v[10:11], v0 offset:33792
	ds_read_b64_tr_b16 v[12:13], v0 offset:34304
	v_cvt_pk_bf16_f32 v8, v124, v210
	v_cvt_pk_bf16_f32 v9, v208, v214
	v_pk_add_f32 v[72:73], v[126:127], v[204:205]
	v_pk_add_f32 v[64:65], v[104:105], v[202:203]
	v_pk_add_f32 v[14:15], v[72:73], v[14:15]
	v_exp_f32_e32 v106, v92
	s_waitcnt lgkmcnt(4)
	v_mfma_f32_32x32x16_bf16 v[16:31], v[68:71], v[6:9], v[16:31]
	v_add_f32_e64 v14, v64, v14
	v_add_f32_e64 v15, v65, v15
	v_add_f32_e64 v64, v212, v120
	v_add_f32_e64 v65, v213, v121
	v_exp_f32_e32 v108, v93
	v_exp_f32_e32 v102, v94
	v_exp_f32_e32 v100, v95
	v_pk_add_f32 v[14:15], v[64:65], v[14:15]
	ds_read_b64_tr_b16 v[64:65], v0 offset:41984
	ds_read_b64_tr_b16 v[66:67], v0 offset:42496
	s_waitcnt lgkmcnt(4)
	v_mfma_f32_32x32x16_bf16 v[32:47], v[2:5], v[6:9], v[32:47]
	v_add_f32_e64 v2, v106, v116
	v_add_f32_e64 v3, v107, v117
	v_cvt_pk_bf16_f32 v4, v106, v108
	v_add_f32_e64 v6, v2, v14
	v_add_f32_e64 v7, v3, v15
	v_cvt_pk_bf16_f32 v2, v122, v126
	v_cvt_pk_bf16_f32 v3, v104, v212
	v_cvt_pk_bf16_f32 v5, v102, v100
	v_pk_add_f32 v[8:9], v[108:109], v[118:119]
	s_waitcnt lgkmcnt(2)
	v_mfma_f32_32x32x16_bf16 v[16:31], v[10:13], v[2:5], v[16:31]
	v_add_f32_e64 v6, v8, v6
	v_add_f32_e64 v7, v9, v7
	v_add_f32_e64 v8, v102, v98
	v_add_f32_e64 v9, v103, v99
	v_pk_add_f32 v[6:7], v[8:9], v[6:7]
	v_pk_add_f32 v[8:9], v[100:101], v[96:97]
	v_pk_add_f32 v[6:7], v[8:9], v[6:7]
	s_waitcnt lgkmcnt(0)
	v_mfma_f32_32x32x16_bf16 v[32:47], v[64:67], v[2:5], v[32:47]
	v_add_f32_e32 v0, v169, v7
	v_add_f32_e32 v0, v6, v0
	s_add_i32 s35, s35, 1
	s_add_i32 s56, s56, 2
	s_add_i32 s6, s46, s35
	v_lshl_add_u64 v[174:175], v[174:175], 0, v[170:171]
	v_lshl_add_u64 v[176:177], v[176:177], 0, s[20:21]
	v_lshl_add_u64 v[178:179], v[178:179], 0, s[20:21]
	v_lshl_add_u64 v[182:183], v[182:183], 0, v[180:181]
	v_lshl_add_u64 v[186:187], v[186:187], 0, v[184:185]
	s_cmp_lg_u32 s6, 1
	v_lshl_add_u64 v[190:191], v[190:191], 0, v[188:189]
	s_waitcnt vmcnt(0) lgkmcnt(0)
	s_barrier
	s_cbranch_scc0 .Lattn_exit_1
	v_mov_b32_e32 v169, v0
	s_bitcmp1_b32 s35, 0
	s_cselect_b32 s6, 0, 0xa800
	s_cmp_ge_u32 s35, s42
	s_cbranch_scc0 .LBB0_856
	s_branch .LBB0_859
.Lattn_exit_1:
	s_nop 7
	s_nop 7
	v_mov_b32_e32 v14, v55
	v_mov_b32_e32 v10, v59
	v_mov_b32_e32 v11, v58
	v_mov_b64_e32 v[110:111], v[30:31]
	v_mov_b32_e32 v6, v63
	v_mov_b32_e32 v7, v62
	v_mov_b32_e32 v8, v61
	v_mov_b32_e32 v9, v60
	v_mov_b64_e32 v[126:127], v[46:47]
	v_mov_b32_e32 v12, v57
	v_mov_b32_e32 v13, v56
	v_mov_b32_e32 v15, v54
	v_mov_b32_e32 v196, v53
	v_mov_b32_e32 v197, v52
	v_mov_b32_e32 v198, v51
	v_mov_b32_e32 v199, v50
	v_mov_b32_e32 v200, v49
	v_mov_b32_e32 v4, v48
	v_mov_b32_e32 v5, v165
	v_mov_b64_e32 v[108:109], v[28:29]
	v_mov_b64_e32 v[106:107], v[26:27]
	v_mov_b64_e32 v[104:105], v[24:25]
	v_mov_b64_e32 v[102:103], v[22:23]
	v_mov_b64_e32 v[100:101], v[20:21]
	v_mov_b64_e32 v[98:99], v[18:19]
	v_mov_b64_e32 v[96:97], v[16:17]
	v_mov_b64_e32 v[124:125], v[44:45]
	v_mov_b64_e32 v[122:123], v[42:43]
	v_mov_b64_e32 v[120:121], v[40:41]
	v_mov_b64_e32 v[118:119], v[38:39]
	v_mov_b64_e32 v[116:117], v[36:37]
	v_mov_b64_e32 v[114:115], v[34:35]
	v_mov_b64_e32 v[112:113], v[32:33]
	s_branch .LBB0_790

; #define LAS __attribute__((address_space(3)))
; __device__ __forceinline__ unsigned cvtpk2(float lo, float hi) { const f32x2 v = {lo, hi}; const bf16x2_n b = __builtin_convertvector(v, bf16x2_n); return __builtin_bit_cast(unsigned, b); }
; __device__ __forceinline__ void a2_exp_pack(f32x16& st0, f32x16& st1, float& lsum, bf16x8 (&pf)[4]) {
;     float ps = 0.f;
; #pragma unroll
;     for (int r = 0; r < 16; ++r) { st0[r] = __builtin_amdgcn_exp2f(st0[r]); st1[r] = __builtin_amdgcn_exp2f(st1[r]); ps += st0[r] + st1[r]; }
;     lsum += ps;
;     u32x4 w;
;     w.x = cvtpk2(st0[0], st0[1]); w.y = cvtpk2(st0[2], st0[3]); w.z = cvtpk2(st0[4], st0[5]); w.w = cvtpk2(st0[6], st0[7]); pf[0] = __builtin_bit_cast(bf16x8, w);
;     w.x = cvtpk2(st0[8], st0[9]); w.y = cvtpk2(st0[10], st0[11]); w.z = cvtpk2(st0[12], st0[13]); w.w = cvtpk2(st0[14], st0[15]); pf[1] = __builtin_bit_cast(bf16x8, w);
;     w.x = cvtpk2(st1[0], st1[1]); w.y = cvtpk2(st1[2], st1[3]); w.z = cvtpk2(st1[4], st1[5]); w.w = cvtpk2(st1[6], st1[7]); pf[2] = __builtin_bit_cast(bf16x8, w);
;     w.x = cvtpk2(st1[8], st1[9]); w.y = cvtpk2(st1[10], st1[11]); w.z = cvtpk2(st1[12], st1[13]); w.w = cvtpk2(st1[14], st1[15]); pf[3] = __builtin_bit_cast(bf16x8, w);
; }
; __device__ __forceinline__ void a2_pv(const LAS unsigned char* vb, const bf16x8 (&pf)[4], f32x16& ot0, f32x16& ot1) {
; #pragma unroll
;     for (int s = 0; s < 4; ++s) {
;         const s16x4 a00 = __builtin_bit_cast(s16x4, __builtin_amdgcn_ds_read_tr16_b64_v4i16((LAS s16x4*)(vb + (16 * s) * 64)));
;         const s16x4 a01 = __builtin_bit_cast(s16x4, __builtin_amdgcn_ds_read_tr16_b64_v4i16((LAS s16x4*)(vb + (16 * s + 8) * 64)));
;         const s16x4 a10 = __builtin_bit_cast(s16x4, __builtin_amdgcn_ds_read_tr16_b64_v4i16((LAS s16x4*)(vb + 8192 + (16 * s) * 64)));
;         const s16x4 a11 = __builtin_bit_cast(s16x4, __builtin_amdgcn_ds_read_tr16_b64_v4i16((LAS s16x4*)(vb + 8192 + (16 * s + 8) * 64)));
;         const bf16x8 va0 = (bf16x8){a00[0], a00[1], a00[2], a00[3], a01[0], a01[1], a01[2], a01[3]};
;         const bf16x8 va1 = (bf16x8){a10[0], a10[1], a10[2], a10[3], a11[0], a11[1], a11[2], a11[3]};
;         ot0 = __builtin_amdgcn_mfma_f32_32x32x16_bf16(va0, pf[s], ot0, 0, 0, 0); ot1 = __builtin_amdgcn_mfma_f32_32x32x16_bf16(va1, pf[s], ot1, 0, 0, 0); }
; }
.LBB0_2243:
	v_add_u32_e32 v0, v2, v218
	v_exp_f32_e32 v199, v112
	v_exp_f32_e32 v7, v96
	v_exp_f32_e32 v113, v113
	v_exp_f32_e32 v9, v97
	v_exp_f32_e32 v201, v114
	v_exp_f32_e32 v3, v98
	v_exp_f32_e32 v115, v115
	v_exp_f32_e32 v5, v99
	v_exp_f32_e32 v203, v116
	v_exp_f32_e32 v15, v117
	v_exp_f32_e32 v13, v118
	v_exp_f32_e32 v11, v119
	s_waitcnt vmcnt(0)
	ds_read_b64_tr_b16 v[96:97], v0 offset:26624
	ds_read_b64_tr_b16 v[98:99], v0 offset:27136
	ds_read_b64_tr_b16 v[214:215], v0 offset:34816
	ds_read_b64_tr_b16 v[216:217], v0 offset:35328
	ds_read_b64_tr_b16 v[220:221], v0 offset:27648
	ds_read_b64_tr_b16 v[222:223], v0 offset:28160
	v_cvt_pk_bf16_f32 v210, v199, v113
	v_cvt_pk_bf16_f32 v211, v201, v115
	v_cvt_pk_bf16_f32 v212, v203, v15
	v_cvt_pk_bf16_f32 v213, v13, v11
	v_exp_f32_e32 v209, v120
	v_exp_f32_e32 v207, v121
	s_waitcnt lgkmcnt(4)
	v_mfma_f32_32x32x16_bf16 v[16:31], v[96:99], v[210:213], v[16:31]
	v_exp_f32_e32 v205, v122
	v_exp_f32_e32 v121, v123
	v_exp_f32_e32 v117, v124
	ds_read_b64_tr_b16 v[224:225], v0 offset:35840
	ds_read_b64_tr_b16 v[226:227], v0 offset:36352
	v_exp_f32_e32 v119, v125
	v_exp_f32_e32 v99, v126
	v_exp_f32_e32 v97, v127
	s_waitcnt lgkmcnt(4)
	v_mfma_f32_32x32x16_bf16 v[32:47], v[214:217], v[210:213], v[32:47]
	v_cvt_pk_bf16_f32 v228, v209, v207
	v_cvt_pk_bf16_f32 v229, v205, v121
	v_cvt_pk_bf16_f32 v230, v117, v119
	v_cvt_pk_bf16_f32 v231, v99, v97
	v_exp_f32_e32 v125, v100
	v_exp_f32_e32 v213, v101
	v_exp_f32_e32 v211, v102
	s_waitcnt lgkmcnt(2)
	v_mfma_f32_32x32x16_bf16 v[16:31], v[220:223], v[228:231], v[16:31]
	v_exp_f32_e32 v217, v103
	ds_read_b64_tr_b16 v[220:221], v0 offset:28672
	ds_read_b64_tr_b16 v[222:223], v0 offset:29184
	v_cvt_pk_bf16_f32 v100, v7, v9
	v_cvt_pk_bf16_f32 v101, v3, v5
	v_cvt_pk_bf16_f32 v102, v125, v213
	v_cvt_pk_bf16_f32 v103, v211, v217
	v_exp_f32_e32 v123, v104
	s_waitcnt lgkmcnt(2)
	v_mfma_f32_32x32x16_bf16 v[32:47], v[224:227], v[228:231], v[32:47]
	ds_read_b64_tr_b16 v[224:225], v0 offset:36864
	ds_read_b64_tr_b16 v[226:227], v0 offset:37376
	ds_read_b64_tr_b16 v[228:229], v0 offset:29696
	ds_read_b64_tr_b16 v[230:231], v0 offset:30208
	v_exp_f32_e32 v127, v105
	v_exp_f32_e32 v105, v106
	v_exp_f32_e32 v215, v107
	v_exp_f32_e32 v107, v108
	v_exp_f32_e32 v109, v109
	v_exp_f32_e32 v198, v64
	s_waitcnt lgkmcnt(4)
	v_mfma_f32_32x32x16_bf16 v[16:31], v[220:223], v[100:103], v[16:31]
	ds_read_b64_tr_b16 v[220:221], v0 offset:37888
	ds_read_b64_tr_b16 v[222:223], v0 offset:38400
	v_exp_f32_e32 v6, v80
	v_exp_f32_e32 v112, v65
	v_exp_f32_e32 v8, v81
	v_exp_f32_e32 v200, v66
	v_exp_f32_e32 v2, v82
	v_exp_f32_e32 v114, v67
	s_waitcnt lgkmcnt(4)
	v_mfma_f32_32x32x16_bf16 v[32:47], v[224:227], v[100:103], v[32:47]
	v_exp_f32_e32 v103, v110
	v_exp_f32_e32 v101, v111
	v_exp_f32_e32 v4, v83
	v_cvt_pk_bf16_f32 v224, v123, v127
	v_cvt_pk_bf16_f32 v225, v105, v215
	v_cvt_pk_bf16_f32 v226, v107, v109
	v_cvt_pk_bf16_f32 v227, v103, v101
	v_pk_add_f32 v[64:65], v[6:7], v[198:199]
	v_pk_add_f32 v[66:67], v[8:9], v[112:113]
	s_waitcnt lgkmcnt(2)
	v_mfma_f32_32x32x16_bf16 v[16:31], v[228:231], v[224:227], v[16:31]
	v_add_f32_e64 v64, v64, 0
	v_add_f32_e64 v65, v65, 0
	v_exp_f32_e32 v202, v68
	v_pk_add_f32 v[64:65], v[66:67], v[64:65]
	v_pk_add_f32 v[66:67], v[2:3], v[200:201]
	v_exp_f32_e32 v14, v69
	v_pk_add_f32 v[64:65], v[66:67], v[64:65]
	v_pk_add_f32 v[66:67], v[4:5], v[114:115]
	s_waitcnt lgkmcnt(0)
	v_mfma_f32_32x32x16_bf16 v[32:47], v[220:223], v[224:227], v[32:47]
	v_add_f32_e64 v110, v66, v64
	v_add_f32_e64 v111, v67, v65
	v_exp_f32_e32 v12, v70
	v_exp_f32_e32 v10, v71
	ds_read_b64_tr_b16 v[64:65], v0 offset:30720
	ds_read_b64_tr_b16 v[66:67], v0 offset:31232
	v_exp_f32_e32 v124, v84
	v_exp_f32_e32 v208, v72
	v_exp_f32_e32 v206, v73
	v_exp_f32_e32 v204, v74
	v_exp_f32_e32 v120, v75
	ds_read_b64_tr_b16 v[72:73], v0 offset:38912
	ds_read_b64_tr_b16 v[74:75], v0 offset:39424
	ds_read_b64_tr_b16 v[80:81], v0 offset:31744
	ds_read_b64_tr_b16 v[82:83], v0 offset:32256
	v_exp_f32_e32 v212, v85
	v_cvt_pk_bf16_f32 v68, v198, v112
	v_cvt_pk_bf16_f32 v69, v200, v114
	v_cvt_pk_bf16_f32 v70, v202, v14
	v_cvt_pk_bf16_f32 v71, v12, v10
	v_pk_add_f32 v[220:221], v[124:125], v[202:203]
	v_exp_f32_e32 v210, v86
	s_waitcnt lgkmcnt(4)
; #define LAS __attribute__((address_space(3)))
; __device__ __forceinline__ void a2_pv(const LAS unsigned char* vb, const bf16x8 (&pf)[4], f32x16& ot0, f32x16& ot1) {
; #pragma unroll
;     for (int s = 0; s < 4; ++s) {
;         const s16x4 a00 = __builtin_bit_cast(s16x4, __builtin_amdgcn_ds_read_tr16_b64_v4i16((LAS s16x4*)(vb + (16 * s) * 64)));
;         const s16x4 a01 = __builtin_bit_cast(s16x4, __builtin_amdgcn_ds_read_tr16_b64_v4i16((LAS s16x4*)(vb + (16 * s + 8) * 64)));
;         const s16x4 a10 = __builtin_bit_cast(s16x4, __builtin_amdgcn_ds_read_tr16_b64_v4i16((LAS s16x4*)(vb + 8192 + (16 * s) * 64)));
;         const s16x4 a11 = __builtin_bit_cast(s16x4, __builtin_amdgcn_ds_read_tr16_b64_v4i16((LAS s16x4*)(vb + 8192 + (16 * s + 8) * 64)));
;         const bf16x8 va0 = (bf16x8){a00[0], a00[1], a00[2], a00[3], a01[0], a01[1], a01[2], a01[3]};
;         const bf16x8 va1 = (bf16x8){a10[0], a10[1], a10[2], a10[3], a11[0], a11[1], a11[2], a11[3]};
;         ot0 = __builtin_amdgcn_mfma_f32_32x32x16_bf16(va0, pf[s], ot0, 0, 0, 0); ot1 = __builtin_amdgcn_mfma_f32_32x32x16_bf16(va1, pf[s], ot1, 0, 0, 0); }
; }
; __device__ __forceinline__ void attn2_unit(bf16_t* Z, const bf16_t* Hb, const float* rc, const float* rs, LAS unsigned char* lds, int b, int h, int qblk) {
;     ...
;             a2_exp_pack(sa0, sa1, lsum, pa);
;             a2_pv(vb, pa, ot0, ot1);
;             a2_exp_pack(sb0, sb1, lsum, pb);
;             a2_pv(vb + 64 * 64, pb, ot0, ot1);
;         } else if (2 * kp <= cw) {
;             f32x16 sa0, sa1; bf16x8 pa[4];
;             a2_qk(kb, qf, cneg, sa0, sa1);
;             const float mt = a2_max(sa0, sa1);
;             if (kp == 0 || __builtin_amdgcn_ballot_w64(mt > 8.f) != 0ull) {
;                 const float delta = (kp == 0) ? mt : fmaxf(mt, 0.f), alpha = (kp == 0) ? 0.f : __builtin_amdgcn_exp2f(-delta);
;                 mrun += delta; lsum *= alpha;
; #pragma unroll
;                 for (int r = 0; r < 16; ++r) { ot0[r] *= alpha; ot1[r] *= alpha; sa0[r] -= delta; sa1[r] -= delta; cneg[r] = -mrun; }
;             }
;             a2_exp_pack(sa0, sa1, lsum, pa);
;             a2_pv(vb, pa, ot0, ot1);
;         }
;         __syncthreads();
;     }
	v_mfma_f32_32x32x16_bf16 v[16:31], v[64:67], v[68:71], v[16:31]
	v_add_f32_e64 v64, v220, v110
	v_add_f32_e64 v65, v221, v111
	v_add_f32_e64 v14, v212, v14
	v_add_f32_e64 v15, v213, v15
	v_exp_f32_e32 v216, v87
	v_exp_f32_e32 v116, v76
	v_exp_f32_e32 v118, v77
	v_exp_f32_e32 v98, v78
	v_exp_f32_e32 v96, v79
	s_waitcnt lgkmcnt(2)
	v_mfma_f32_32x32x16_bf16 v[32:47], v[72:75], v[68:71], v[32:47]
	v_add_f32_e64 v14, v14, v64
	v_add_f32_e64 v15, v15, v65
	ds_read_b64_tr_b16 v[64:65], v0 offset:39936
	ds_read_b64_tr_b16 v[66:67], v0 offset:40448
	v_exp_f32_e32 v122, v88
	v_pk_add_f32 v[12:13], v[210:211], v[12:13]
	v_pk_add_f32 v[68:69], v[216:217], v[10:11]
	v_pk_add_f32 v[14:15], v[12:13], v[14:15]
	v_cvt_pk_bf16_f32 v10, v208, v206
	v_cvt_pk_bf16_f32 v11, v204, v120
	v_cvt_pk_bf16_f32 v12, v116, v118
	v_cvt_pk_bf16_f32 v13, v98, v96
	v_pk_add_f32 v[14:15], v[68:69], v[14:15]
	v_pk_add_f32 v[68:69], v[122:123], v[208:209]
	s_waitcnt lgkmcnt(2)
	v_mfma_f32_32x32x16_bf16 v[16:31], v[80:83], v[10:13], v[16:31]
	v_add_f32_e64 v14, v68, v14
	v_add_f32_e64 v15, v69, v15
	ds_read_b64_tr_b16 v[68:69], v0 offset:32768
	ds_read_b64_tr_b16 v[70:71], v0 offset:33280
	v_exp_f32_e32 v126, v89
	v_exp_f32_e32 v104, v90
	v_cvt_pk_bf16_f32 v7, v2, v4
	v_exp_f32_e32 v214, v91
	v_cvt_pk_bf16_f32 v6, v6, v8
	s_waitcnt lgkmcnt(2)
	v_mfma_f32_32x32x16_bf16 v[32:47], v[64:67], v[10:13], v[32:47]
	ds_read_b64_tr_b16 v[2:3], v0 offset:40960
	ds_read_b64_tr_b16 v[4:5], v0 offset:41472
	ds_read_b64_tr_b16 v[10:11], v0 offset:33792
	ds_read_b64_tr_b16 v[12:13], v0 offset:34304
	v_cvt_pk_bf16_f32 v8, v124, v212
	v_cvt_pk_bf16_f32 v9, v210, v216
	v_pk_add_f32 v[72:73], v[126:127], v[206:207]
	v_pk_add_f32 v[64:65], v[104:105], v[204:205]
	v_pk_add_f32 v[14:15], v[72:73], v[14:15]
	v_exp_f32_e32 v106, v92
	s_waitcnt lgkmcnt(4)
	v_mfma_f32_32x32x16_bf16 v[16:31], v[68:71], v[6:9], v[16:31]
	v_add_f32_e64 v14, v64, v14
	v_add_f32_e64 v15, v65, v15
	v_add_f32_e64 v64, v214, v120
	v_add_f32_e64 v65, v215, v121
	v_exp_f32_e32 v108, v93
	v_exp_f32_e32 v102, v94
	v_exp_f32_e32 v100, v95
	v_pk_add_f32 v[14:15], v[64:65], v[14:15]
	ds_read_b64_tr_b16 v[64:65], v0 offset:41984
	ds_read_b64_tr_b16 v[66:67], v0 offset:42496
	s_waitcnt lgkmcnt(4)
	v_mfma_f32_32x32x16_bf16 v[32:47], v[2:5], v[6:9], v[32:47]
	v_add_f32_e64 v2, v106, v116
	v_add_f32_e64 v3, v107, v117
	v_cvt_pk_bf16_f32 v4, v106, v108
	v_add_f32_e64 v6, v2, v14
	v_add_f32_e64 v7, v3, v15
	v_cvt_pk_bf16_f32 v2, v122, v126
	v_cvt_pk_bf16_f32 v3, v104, v214
	v_cvt_pk_bf16_f32 v5, v102, v100
	v_pk_add_f32 v[8:9], v[108:109], v[118:119]
	s_waitcnt lgkmcnt(2)
	v_mfma_f32_32x32x16_bf16 v[16:31], v[10:13], v[2:5], v[16:31]
	v_add_f32_e64 v6, v8, v6
	v_add_f32_e64 v7, v9, v7
	v_add_f32_e64 v8, v102, v98
	v_add_f32_e64 v9, v103, v99
	v_pk_add_f32 v[6:7], v[8:9], v[6:7]
	v_pk_add_f32 v[8:9], v[100:101], v[96:97]
	v_pk_add_f32 v[6:7], v[8:9], v[6:7]
	s_waitcnt lgkmcnt(0)
	v_mfma_f32_32x32x16_bf16 v[32:47], v[64:67], v[2:5], v[32:47]
	v_add_f32_e32 v0, v169, v7
	v_add_f32_e32 v0, v6, v0
	s_add_i32 s47, s47, 1
	s_add_i32 s48, s48, 2
	s_add_i32 s6, s37, s47
	v_lshl_add_u64 v[176:177], v[176:177], 0, v[174:175]
	v_lshl_add_u64 v[178:179], v[178:179], 0, s[18:19]
	v_lshl_add_u64 v[180:181], v[180:181], 0, s[18:19]
	v_lshl_add_u64 v[184:185], v[184:185], 0, v[182:183]
	v_lshl_add_u64 v[188:189], v[188:189], 0, v[186:187]
	s_cmp_lg_u32 s6, 1
	v_lshl_add_u64 v[194:195], v[194:195], 0, v[190:191]
	s_waitcnt vmcnt(0) lgkmcnt(0)
	s_barrier
	s_cbranch_scc0 .Lattn_exit_2
	v_mov_b32_e32 v169, v0
	s_bitcmp1_b32 s47, 0
	s_cselect_b32 s6, 0, 0xa800
	s_cmp_ge_u32 s47, s34
	s_cbranch_scc0 .LBB0_2221
	s_branch .LBB0_2224

; #define LAS __attribute__((address_space(3)))
; __device__ __forceinline__ unsigned cvtpk2(float lo, float hi) { const f32x2 v = {lo, hi}; const bf16x2_n b = __builtin_convertvector(v, bf16x2_n); return __builtin_bit_cast(unsigned, b); }
; __device__ __forceinline__ void a2_exp_pack(f32x16& st0, f32x16& st1, float& lsum, bf16x8 (&pf)[4]) {
;     float ps = 0.f;
; #pragma unroll
;     for (int r = 0; r < 16; ++r) { st0[r] = __builtin_amdgcn_exp2f(st0[r]); st1[r] = __builtin_amdgcn_exp2f(st1[r]); ps += st0[r] + st1[r]; }
;     lsum += ps;
;     u32x4 w;
;     w.x = cvtpk2(st0[0], st0[1]); w.y = cvtpk2(st0[2], st0[3]); w.z = cvtpk2(st0[4], st0[5]); w.w = cvtpk2(st0[6], st0[7]); pf[0] = __builtin_bit_cast(bf16x8, w);
;     w.x = cvtpk2(st0[8], st0[9]); w.y = cvtpk2(st0[10], st0[11]); w.z = cvtpk2(st0[12], st0[13]); w.w = cvtpk2(st0[14], st0[15]); pf[1] = __builtin_bit_cast(bf16x8, w);
;     w.x = cvtpk2(st1[0], st1[1]); w.y = cvtpk2(st1[2], st1[3]); w.z = cvtpk2(st1[4], st1[5]); w.w = cvtpk2(st1[6], st1[7]); pf[2] = __builtin_bit_cast(bf16x8, w);
;     w.x = cvtpk2(st1[8], st1[9]); w.y = cvtpk2(st1[10], st1[11]); w.z = cvtpk2(st1[12], st1[13]); w.w = cvtpk2(st1[14], st1[15]); pf[3] = __builtin_bit_cast(bf16x8, w);
; }
; __device__ __forceinline__ void a2_pv(const LAS unsigned char* vb, const bf16x8 (&pf)[4], f32x16& ot0, f32x16& ot1) {
; #pragma unroll
;     for (int s = 0; s < 4; ++s) {
;         const s16x4 a00 = __builtin_bit_cast(s16x4, __builtin_amdgcn_ds_read_tr16_b64_v4i16((LAS s16x4*)(vb + (16 * s) * 64)));
;         const s16x4 a01 = __builtin_bit_cast(s16x4, __builtin_amdgcn_ds_read_tr16_b64_v4i16((LAS s16x4*)(vb + (16 * s + 8) * 64)));
;         const s16x4 a10 = __builtin_bit_cast(s16x4, __builtin_amdgcn_ds_read_tr16_b64_v4i16((LAS s16x4*)(vb + 8192 + (16 * s) * 64)));
;         const s16x4 a11 = __builtin_bit_cast(s16x4, __builtin_amdgcn_ds_read_tr16_b64_v4i16((LAS s16x4*)(vb + 8192 + (16 * s + 8) * 64)));
;         const bf16x8 va0 = (bf16x8){a00[0], a00[1], a00[2], a00[3], a01[0], a01[1], a01[2], a01[3]};
;         const bf16x8 va1 = (bf16x8){a10[0], a10[1], a10[2], a10[3], a11[0], a11[1], a11[2], a11[3]};
;         ot0 = __builtin_amdgcn_mfma_f32_32x32x16_bf16(va0, pf[s], ot0, 0, 0, 0); ot1 = __builtin_amdgcn_mfma_f32_32x32x16_bf16(va1, pf[s], ot1, 0, 0, 0); }
; }
.LBB0_2289:
	v_add_u32_e32 v0, v2, v218
	v_exp_f32_e32 v195, v112
	v_exp_f32_e32 v7, v96
	v_exp_f32_e32 v113, v113
	v_exp_f32_e32 v9, v97
	v_exp_f32_e32 v199, v114
	v_exp_f32_e32 v3, v98
	v_exp_f32_e32 v115, v115
	v_exp_f32_e32 v5, v99
	v_exp_f32_e32 v201, v116
	v_exp_f32_e32 v15, v117
	v_exp_f32_e32 v13, v118
	v_exp_f32_e32 v11, v119
	s_waitcnt vmcnt(0)
	ds_read_b64_tr_b16 v[96:97], v0 offset:26624
	ds_read_b64_tr_b16 v[98:99], v0 offset:27136
	ds_read_b64_tr_b16 v[212:213], v0 offset:34816
	ds_read_b64_tr_b16 v[214:215], v0 offset:35328
	ds_read_b64_tr_b16 v[220:221], v0 offset:27648
	ds_read_b64_tr_b16 v[222:223], v0 offset:28160
	v_cvt_pk_bf16_f32 v208, v195, v113
	v_cvt_pk_bf16_f32 v209, v199, v115
	v_cvt_pk_bf16_f32 v210, v201, v15
	v_cvt_pk_bf16_f32 v211, v13, v11
	v_exp_f32_e32 v207, v120
	v_exp_f32_e32 v205, v121
	s_waitcnt lgkmcnt(4)
	v_mfma_f32_32x32x16_bf16 v[16:31], v[96:99], v[208:211], v[16:31]
	v_exp_f32_e32 v203, v122
	v_exp_f32_e32 v121, v123
	v_exp_f32_e32 v117, v124
	ds_read_b64_tr_b16 v[224:225], v0 offset:35840
	ds_read_b64_tr_b16 v[226:227], v0 offset:36352
	v_exp_f32_e32 v119, v125
	v_exp_f32_e32 v99, v126
	v_exp_f32_e32 v97, v127
	s_waitcnt lgkmcnt(4)
	v_mfma_f32_32x32x16_bf16 v[32:47], v[212:215], v[208:211], v[32:47]
	v_cvt_pk_bf16_f32 v228, v207, v205
	v_cvt_pk_bf16_f32 v229, v203, v121
	v_cvt_pk_bf16_f32 v230, v117, v119
	v_cvt_pk_bf16_f32 v231, v99, v97
	v_exp_f32_e32 v125, v100
	v_exp_f32_e32 v211, v101
	v_exp_f32_e32 v209, v102
	s_waitcnt lgkmcnt(2)
	v_mfma_f32_32x32x16_bf16 v[16:31], v[220:223], v[228:231], v[16:31]
	v_exp_f32_e32 v215, v103
	ds_read_b64_tr_b16 v[220:221], v0 offset:28672
	ds_read_b64_tr_b16 v[222:223], v0 offset:29184
	v_cvt_pk_bf16_f32 v100, v7, v9
	v_cvt_pk_bf16_f32 v101, v3, v5
	v_cvt_pk_bf16_f32 v102, v125, v211
	v_cvt_pk_bf16_f32 v103, v209, v215
	v_exp_f32_e32 v123, v104
	s_waitcnt lgkmcnt(2)
	v_mfma_f32_32x32x16_bf16 v[32:47], v[224:227], v[228:231], v[32:47]
	ds_read_b64_tr_b16 v[224:225], v0 offset:36864
	ds_read_b64_tr_b16 v[226:227], v0 offset:37376
	ds_read_b64_tr_b16 v[228:229], v0 offset:29696
	ds_read_b64_tr_b16 v[230:231], v0 offset:30208
	v_exp_f32_e32 v127, v105
	v_exp_f32_e32 v105, v106
	v_exp_f32_e32 v213, v107
	v_exp_f32_e32 v107, v108
	v_exp_f32_e32 v109, v109
	v_exp_f32_e32 v194, v64
	s_waitcnt lgkmcnt(4)
	v_mfma_f32_32x32x16_bf16 v[16:31], v[220:223], v[100:103], v[16:31]
	ds_read_b64_tr_b16 v[220:221], v0 offset:37888
	ds_read_b64_tr_b16 v[222:223], v0 offset:38400
	v_exp_f32_e32 v6, v80
	v_exp_f32_e32 v112, v65
	v_exp_f32_e32 v8, v81
	v_exp_f32_e32 v198, v66
	v_exp_f32_e32 v2, v82
	v_exp_f32_e32 v114, v67
	s_waitcnt lgkmcnt(4)
	v_mfma_f32_32x32x16_bf16 v[32:47], v[224:227], v[100:103], v[32:47]
	v_exp_f32_e32 v103, v110
	v_exp_f32_e32 v101, v111
	v_exp_f32_e32 v4, v83
	v_cvt_pk_bf16_f32 v224, v123, v127
	v_cvt_pk_bf16_f32 v225, v105, v213
	v_cvt_pk_bf16_f32 v226, v107, v109
	v_cvt_pk_bf16_f32 v227, v103, v101
	v_pk_add_f32 v[64:65], v[6:7], v[194:195]
	v_pk_add_f32 v[66:67], v[8:9], v[112:113]
	s_waitcnt lgkmcnt(2)
	v_mfma_f32_32x32x16_bf16 v[16:31], v[228:231], v[224:227], v[16:31]
	v_add_f32_e64 v64, v64, 0
	v_add_f32_e64 v65, v65, 0
	v_exp_f32_e32 v200, v68
	v_pk_add_f32 v[64:65], v[66:67], v[64:65]
	v_pk_add_f32 v[66:67], v[2:3], v[198:199]
	v_exp_f32_e32 v14, v69
	v_pk_add_f32 v[64:65], v[66:67], v[64:65]
	v_pk_add_f32 v[66:67], v[4:5], v[114:115]
	s_waitcnt lgkmcnt(0)
	v_mfma_f32_32x32x16_bf16 v[32:47], v[220:223], v[224:227], v[32:47]
	v_add_f32_e64 v110, v66, v64
	v_add_f32_e64 v111, v67, v65
	v_exp_f32_e32 v12, v70
	v_exp_f32_e32 v10, v71
	ds_read_b64_tr_b16 v[64:65], v0 offset:30720
	ds_read_b64_tr_b16 v[66:67], v0 offset:31232
	v_exp_f32_e32 v124, v84
	v_exp_f32_e32 v206, v72
	v_exp_f32_e32 v204, v73
	v_exp_f32_e32 v202, v74
	v_exp_f32_e32 v120, v75
	ds_read_b64_tr_b16 v[72:73], v0 offset:38912
	ds_read_b64_tr_b16 v[74:75], v0 offset:39424
	ds_read_b64_tr_b16 v[80:81], v0 offset:31744
	ds_read_b64_tr_b16 v[82:83], v0 offset:32256
	v_exp_f32_e32 v210, v85
	v_cvt_pk_bf16_f32 v68, v194, v112
	v_cvt_pk_bf16_f32 v69, v198, v114
	v_cvt_pk_bf16_f32 v70, v200, v14
	v_cvt_pk_bf16_f32 v71, v12, v10
	v_pk_add_f32 v[216:217], v[124:125], v[200:201]
	v_exp_f32_e32 v208, v86
	s_waitcnt lgkmcnt(4)
	v_mfma_f32_32x32x16_bf16 v[16:31], v[64:67], v[68:71], v[16:31]
	v_add_f32_e64 v64, v216, v110
	v_add_f32_e64 v65, v217, v111
	v_add_f32_e64 v14, v210, v14
	v_add_f32_e64 v15, v211, v15
	v_exp_f32_e32 v214, v87
	v_exp_f32_e32 v116, v76
	v_exp_f32_e32 v118, v77
	v_exp_f32_e32 v98, v78
	v_exp_f32_e32 v96, v79
	s_waitcnt lgkmcnt(2)
; #define LAS __attribute__((address_space(3)))
; __device__ __forceinline__ void a2_pv(const LAS unsigned char* vb, const bf16x8 (&pf)[4], f32x16& ot0, f32x16& ot1) {
; #pragma unroll
;     for (int s = 0; s < 4; ++s) {
;         const s16x4 a00 = __builtin_bit_cast(s16x4, __builtin_amdgcn_ds_read_tr16_b64_v4i16((LAS s16x4*)(vb + (16 * s) * 64)));
;         const s16x4 a01 = __builtin_bit_cast(s16x4, __builtin_amdgcn_ds_read_tr16_b64_v4i16((LAS s16x4*)(vb + (16 * s + 8) * 64)));
;         const s16x4 a10 = __builtin_bit_cast(s16x4, __builtin_amdgcn_ds_read_tr16_b64_v4i16((LAS s16x4*)(vb + 8192 + (16 * s) * 64)));
;         const s16x4 a11 = __builtin_bit_cast(s16x4, __builtin_amdgcn_ds_read_tr16_b64_v4i16((LAS s16x4*)(vb + 8192 + (16 * s + 8) * 64)));
;         const bf16x8 va0 = (bf16x8){a00[0], a00[1], a00[2], a00[3], a01[0], a01[1], a01[2], a01[3]};
;         const bf16x8 va1 = (bf16x8){a10[0], a10[1], a10[2], a10[3], a11[0], a11[1], a11[2], a11[3]};
;         ot0 = __builtin_amdgcn_mfma_f32_32x32x16_bf16(va0, pf[s], ot0, 0, 0, 0); ot1 = __builtin_amdgcn_mfma_f32_32x32x16_bf16(va1, pf[s], ot1, 0, 0, 0); }
; }
; __device__ __forceinline__ void attn2_unit(bf16_t* Z, const bf16_t* Hb, const float* rc, const float* rs, LAS unsigned char* lds, int b, int h, int qblk) {
;     ...
;             a2_exp_pack(sa0, sa1, lsum, pa);
;             a2_pv(vb, pa, ot0, ot1);
;             a2_exp_pack(sb0, sb1, lsum, pb);
;             a2_pv(vb + 64 * 64, pb, ot0, ot1);
;         } else if (2 * kp <= cw) {
;             f32x16 sa0, sa1; bf16x8 pa[4];
;             a2_qk(kb, qf, cneg, sa0, sa1);
;             const float mt = a2_max(sa0, sa1);
;             if (kp == 0 || __builtin_amdgcn_ballot_w64(mt > 8.f) != 0ull) {
;                 const float delta = (kp == 0) ? mt : fmaxf(mt, 0.f), alpha = (kp == 0) ? 0.f : __builtin_amdgcn_exp2f(-delta);
;                 mrun += delta; lsum *= alpha;
; #pragma unroll
;                 for (int r = 0; r < 16; ++r) { ot0[r] *= alpha; ot1[r] *= alpha; sa0[r] -= delta; sa1[r] -= delta; cneg[r] = -mrun; }
;             }
;             a2_exp_pack(sa0, sa1, lsum, pa);
;             a2_pv(vb, pa, ot0, ot1);
;         }
;         __syncthreads();
;     }
	v_mfma_f32_32x32x16_bf16 v[32:47], v[72:75], v[68:71], v[32:47]
	v_add_f32_e64 v14, v14, v64
	v_add_f32_e64 v15, v15, v65
	ds_read_b64_tr_b16 v[64:65], v0 offset:39936
	ds_read_b64_tr_b16 v[66:67], v0 offset:40448
	v_exp_f32_e32 v122, v88
	v_pk_add_f32 v[12:13], v[208:209], v[12:13]
	v_pk_add_f32 v[68:69], v[214:215], v[10:11]
	v_pk_add_f32 v[14:15], v[12:13], v[14:15]
	v_cvt_pk_bf16_f32 v10, v206, v204
	v_cvt_pk_bf16_f32 v11, v202, v120
	v_cvt_pk_bf16_f32 v12, v116, v118
	v_cvt_pk_bf16_f32 v13, v98, v96
	v_pk_add_f32 v[14:15], v[68:69], v[14:15]
	v_pk_add_f32 v[68:69], v[122:123], v[206:207]
	s_waitcnt lgkmcnt(2)
	v_mfma_f32_32x32x16_bf16 v[16:31], v[80:83], v[10:13], v[16:31]
	v_add_f32_e64 v14, v68, v14
	v_add_f32_e64 v15, v69, v15
	ds_read_b64_tr_b16 v[68:69], v0 offset:32768
	ds_read_b64_tr_b16 v[70:71], v0 offset:33280
	v_exp_f32_e32 v126, v89
	v_exp_f32_e32 v104, v90
	v_cvt_pk_bf16_f32 v7, v2, v4
	v_exp_f32_e32 v212, v91
	v_cvt_pk_bf16_f32 v6, v6, v8
	s_waitcnt lgkmcnt(2)
	v_mfma_f32_32x32x16_bf16 v[32:47], v[64:67], v[10:13], v[32:47]
	ds_read_b64_tr_b16 v[2:3], v0 offset:40960
	ds_read_b64_tr_b16 v[4:5], v0 offset:41472
	ds_read_b64_tr_b16 v[10:11], v0 offset:33792
	ds_read_b64_tr_b16 v[12:13], v0 offset:34304
	v_cvt_pk_bf16_f32 v8, v124, v210
	v_cvt_pk_bf16_f32 v9, v208, v214
	v_pk_add_f32 v[72:73], v[126:127], v[204:205]
	v_pk_add_f32 v[64:65], v[104:105], v[202:203]
	v_pk_add_f32 v[14:15], v[72:73], v[14:15]
	v_exp_f32_e32 v106, v92
	s_waitcnt lgkmcnt(4)
	v_mfma_f32_32x32x16_bf16 v[16:31], v[68:71], v[6:9], v[16:31]
	v_add_f32_e64 v14, v64, v14
	v_add_f32_e64 v15, v65, v15
	v_add_f32_e64 v64, v212, v120
	v_add_f32_e64 v65, v213, v121
	v_exp_f32_e32 v108, v93
	v_exp_f32_e32 v102, v94
	v_exp_f32_e32 v100, v95
	v_pk_add_f32 v[14:15], v[64:65], v[14:15]
	ds_read_b64_tr_b16 v[64:65], v0 offset:41984
	ds_read_b64_tr_b16 v[66:67], v0 offset:42496
	s_waitcnt lgkmcnt(4)
	v_mfma_f32_32x32x16_bf16 v[32:47], v[2:5], v[6:9], v[32:47]
	v_add_f32_e64 v2, v106, v116
	v_add_f32_e64 v3, v107, v117
	v_cvt_pk_bf16_f32 v4, v106, v108
	v_add_f32_e64 v6, v2, v14
	v_add_f32_e64 v7, v3, v15
	v_cvt_pk_bf16_f32 v2, v122, v126
	v_cvt_pk_bf16_f32 v3, v104, v212
	v_cvt_pk_bf16_f32 v5, v102, v100
	v_pk_add_f32 v[8:9], v[108:109], v[118:119]
	s_waitcnt lgkmcnt(2)
	v_mfma_f32_32x32x16_bf16 v[16:31], v[10:13], v[2:5], v[16:31]
	v_add_f32_e64 v6, v8, v6
	v_add_f32_e64 v7, v9, v7
	v_add_f32_e64 v8, v102, v98
	v_add_f32_e64 v9, v103, v99
	v_pk_add_f32 v[6:7], v[8:9], v[6:7]
	v_pk_add_f32 v[8:9], v[100:101], v[96:97]
	v_pk_add_f32 v[6:7], v[8:9], v[6:7]
	s_waitcnt lgkmcnt(0)
	v_mfma_f32_32x32x16_bf16 v[32:47], v[64:67], v[2:5], v[32:47]
	v_add_f32_e32 v0, v169, v7
	v_add_f32_e32 v0, v6, v0
	s_add_i32 s31, s31, 1
	s_add_i32 s42, s42, 2
	s_add_i32 s6, s38, s31
	v_lshl_add_u64 v[174:175], v[174:175], 0, v[170:171]
	v_lshl_add_u64 v[176:177], v[176:177], 0, s[18:19]
	v_lshl_add_u64 v[178:179], v[178:179], 0, s[18:19]
	v_lshl_add_u64 v[182:183], v[182:183], 0, v[180:181]
	v_lshl_add_u64 v[186:187], v[186:187], 0, v[184:185]
	s_cmp_lg_u32 s6, 1
	v_lshl_add_u64 v[190:191], v[190:191], 0, v[188:189]
	s_waitcnt vmcnt(0) lgkmcnt(0)
	s_barrier
	s_cbranch_scc0 .Lattn_exit_3
	v_mov_b32_e32 v169, v0
	s_bitcmp1_b32 s31, 0
	s_cselect_b32 s6, 0, 0xa800
	s_cmp_ge_u32 s31, s36
	s_cbranch_scc0 .LBB0_2267
	s_branch .LBB0_2270
.Lattn_exit_3:
	s_nop 7
	s_nop 7
	v_mov_b32_e32 v14, v55
	v_mov_b32_e32 v10, v59
	v_mov_b32_e32 v11, v58
	v_mov_b64_e32 v[110:111], v[30:31]
	v_mov_b32_e32 v6, v63
	v_mov_b32_e32 v7, v62
	v_mov_b32_e32 v8, v61
	v_mov_b32_e32 v9, v60
	v_mov_b64_e32 v[126:127], v[46:47]
	v_mov_b32_e32 v12, v57
	v_mov_b32_e32 v13, v56
	v_mov_b32_e32 v15, v54
	v_mov_b32_e32 v194, v53
	v_mov_b32_e32 v195, v52
	v_mov_b32_e32 v198, v51
	v_mov_b32_e32 v199, v50
	v_mov_b32_e32 v200, v49
	v_mov_b32_e32 v4, v48
	v_mov_b32_e32 v5, v165
	v_mov_b64_e32 v[108:109], v[28:29]
	v_mov_b64_e32 v[106:107], v[26:27]
	v_mov_b64_e32 v[104:105], v[24:25]
	v_mov_b64_e32 v[102:103], v[22:23]
	v_mov_b64_e32 v[100:101], v[20:21]
	v_mov_b64_e32 v[98:99], v[18:19]
	v_mov_b64_e32 v[96:97], v[16:17]
	v_mov_b64_e32 v[124:125], v[44:45]
	v_mov_b64_e32 v[122:123], v[42:43]
	v_mov_b64_e32 v[120:121], v[40:41]
	v_mov_b64_e32 v[118:119], v[38:39]
	v_mov_b64_e32 v[116:117], v[36:37]
	v_mov_b64_e32 v[114:115], v[34:35]
	v_mov_b64_e32 v[112:113], v[32:33]
	s_branch .LBB0_2201
